# windowed and neighbourhood attention loops: K/V staging addresses hoisted out of the loop (SGPR tile base + invariant lane offset), on top of v32
# speedup vs baseline: 1.0173x; 1.0033x over previous
; template <int DK, int DV, int MODE>
; DI void att_gload(const AttArgs& a, int tile, u32x4 (&kr)[(64 * (DK / 8) + NT - 1) / NT], u32x4 (&vr)[(64 * (DV / 8) + NT - 1) / NT]) {
;   constexpr int CK = DK / 8, CV = DV / 8;
;   constexpr int NKL = (64 * CK + NT - 1) / NT, NVL = (64 * CV + NT - 1) / NT;
;   const int t = tid_opaque();
;   const int kbase = tile * 64;
; #pragma unroll
;   for (int i = 0; i < NKL; ++i) {
;     const int id = min(t + NT * i, 64 * CK - 1);
;     const int row = id / CK, c = id % CK;
;     if constexpr (MODE == 3) {
;       const bf16_t* src = (c < 8) ? (a.k + (size_t)(kbase + row) * a.ldk + c * 8) : (a.k2 + (size_t)(kbase + row) * a.ldk2 + (c - 8) * 8);
;       kr[i] = *(const u32x4*)src;
;     } else {
;       kr[i] = *(const u32x4*)(a.k + (size_t)(kbase + row) * a.ldk + c * 8);
;     }
; template <int DK, int DV, int MODE, int QB, bool PACK = false>
; DI void attn_item(const AttArgs& a, int q0, int t_lo, int t_hi) {
;     ...
;   if constexpr (MODE == 2) {
;     rq = wq0 >> 6;
;     r0 = min(max(rq - 4, 0), 24);
; #pragma unroll
;     for (int qb = 0; qb < QB; ++qb) {
;       cq[qb] = ((wq0 + qb * 32) & 63) + r;
;       c0[qb] = min(max(cq[qb] - 8, 0), 48);
;     }
;     for (int i = t; i < 465; i += NT) rpbs[i] = a.rpb[i];
;   }
;   bf16x8 qf[QB][NKS];
; #pragma unroll
;   for (int qb = 0; qb < QB; ++qb) {
;     const bf16_t* qp = a.q + hg * DK + (size_t)(wq0 + qb * 32 + r) * a.ldq + h * 8;
; #pragma unroll
;     for (int s = 0; s < NKS; ++s) qf[qb][s] = *(const bf16x8*)(qp + s * 16);
;   }
;   f32x16 o[QB][NDB];
;   float m[QB], lsum[QB];
; #pragma unroll
;   for (int qb = 0; qb < QB; ++qb) {
;     m[qb] = -1e30f; lsum[qb] = 0.f;
; #pragma unroll
;     for (int d = 0; d < NDB; ++d)
; #pragma unroll
;       for (int i = 0; i < 16; ++i) o[qb][d][i] = 0.f;
;   }
;   u32x4 kr[NKL], vr[NVL];
;   att_gload<DK, DV, MODE>(a, t_lo, kr, vr);
;   att_swrite<DK, DV>(0, kr, vr);
;   if (t_lo + 1 < t_hi) att_gload<DK, DV, MODE>(a, t_lo + 1, kr, vr);
;   __syncthreads();
;   const float scale = a.scale;
;   const float cexp = (MODE == 2) ? LOG2E : a.scale * LOG2E;
;   const int vq = (l & 15) >> 2, vp = l & 3, vblk = (l >> 4) & 1;
;   for (int tile = t_lo; tile < t_hi; ++tile) {
;     const int buf = (tile - t_lo) & 1;
;     if (tile + 1 < t_hi) att_swrite<DK, DV>(buf ^ 1, kr, vr);
;     if (tile + 2 < t_hi) att_gload<DK, DV, MODE>(a, tile + 2, kr, vr);
.LBB0_651:
	s_cmp_ge_u32 s33, s27
	s_waitcnt lgkmcnt(0)
	s_barrier
	s_cbranch_scc1 .LBB0_749
	s_and_b32 s0, s29, 3
	v_writelane_b32 v254, s24, 54
	s_lshl_b32 s0, s0, 3
	s_max_u32 s1, s0, 4
	v_writelane_b32 v254, s25, 55
	v_writelane_b32 v254, s21, 56
	v_ashrrev_i32_e32 v3, 6, v3
	s_cmp_gt_u32 s0, 4
	v_writelane_b32 v254, s20, 57
	v_max_i32_e32 v4, 4, v3
	s_cselect_b32 s0, s0, 4
	v_writelane_b32 v254, s38, 58
	v_add_u32_e32 v4, -4, v4
	v_sub_u32_e64 v5, v1, 8 clamp
	s_lshl_b32 s0, s0, 6
	v_lshlrev_b32_e32 v9, 2, v178
	v_min_u32_e32 v179, 24, v4
	v_writelane_b32 v254, s29, 59
	s_mul_i32 s8, s1, 0x7c
	s_add_u32 s2, s0, 0xffffff80
	v_and_b32_e32 v4, 16, v0
	v_lshrrev_b32_e32 v8, 2, v0
	v_lshlrev_b32_e32 v0, 2, v0
	v_cmp_ge_u32_e64 s[0:1], v9, v5
	v_and_or_b32 v0, v0, 12, v4
	v_or_b32_e32 v4, 1, v9
	v_writelane_b32 v254, s0, 60
	v_lshlrev_b32_e32 v181, 1, v0
	v_add_u32_e32 v0, 16, v5
	v_writelane_b32 v254, s1, 61
	v_cmp_ge_u32_e64 s[0:1], v4, v5
	v_or_b32_e32 v4, 2, v9
	v_cmp_lt_u32_e32 vcc, v9, v5
	v_writelane_b32 v254, s0, 62
	s_addc_u32 s3, 0, -1
	v_min_u32_e32 v6, 24, v1
	v_writelane_b32 v254, s1, 63
	v_cmp_ge_u32_e64 s[0:1], v4, v5
	v_or_b32_e32 v4, 3, v9
	v_or_b32_e32 v10, 27, v9
	v_writelane_b32 v255, s0, 0
	v_or_b32_e32 v11, 32, v9
	v_or_b32_e32 v12, 33, v9
	v_writelane_b32 v255, s1, 1
	v_cmp_ge_u32_e64 s[0:1], v4, v5
	v_or_b32_e32 v4, 8, v9
	v_or_b32_e32 v13, 34, v9
	v_writelane_b32 v255, s0, 2
	v_or_b32_e32 v14, 35, v9
	v_add_u32_e32 v7, 24, v6
	v_writelane_b32 v255, s1, 3
	v_cmp_ge_u32_e64 s[0:1], v4, v5
	v_or_b32_e32 v4, 9, v9
	v_cmp_lt_u32_e64 s[60:61], v10, v0
	v_writelane_b32 v255, s0, 4
	v_cmp_lt_u32_e64 s[62:63], v11, v0
	v_cmp_lt_u32_e64 s[64:65], v12, v0
	v_writelane_b32 v255, s1, 5
	v_cmp_ge_u32_e64 s[0:1], v4, v5
	v_or_b32_e32 v4, 10, v9
	v_cmp_lt_u32_e64 s[66:67], v13, v0
	v_writelane_b32 v255, s0, 6
	v_cmp_lt_u32_e64 s[68:69], v14, v0
	v_or_b32_e32 v15, 41, v9
	v_writelane_b32 v255, s1, 7
	v_cmp_ge_u32_e64 s[0:1], v4, v5
	v_or_b32_e32 v4, 11, v9
	v_add_u32_e32 v26, 40, v6
	v_writelane_b32 v255, s0, 8
	v_mul_u32_u24_e32 v182, 0x90, v1
	v_or_b32_e32 v16, 42, v9
	v_writelane_b32 v255, s1, 9
	v_cmp_ge_u32_e64 s[0:1], v4, v5
	v_or_b32_e32 v4, 16, v9
	v_cmp_ge_u32_e64 s[4:5], v4, v5
	v_writelane_b32 v255, s0, 10
	v_or_b32_e32 v4, 17, v9
	v_lshlrev_b32_e32 v1, 2, v1
	v_writelane_b32 v255, s1, 11
	s_and_b64 s[0:1], s[4:5], vcc
	v_cmp_ge_u32_e32 vcc, v4, v5
	v_cmp_lt_u32_e64 s[4:5], v4, v0
	v_or_b32_e32 v4, 18, v9
	s_and_b64 s[24:25], vcc, s[4:5]
	v_cmp_ge_u32_e32 vcc, v4, v5
	v_cmp_lt_u32_e64 s[4:5], v4, v0
	v_or_b32_e32 v4, 19, v9
	s_and_b64 s[52:53], vcc, s[4:5]
	v_cmp_ge_u32_e32 vcc, v4, v5
	v_cmp_lt_u32_e64 s[4:5], v4, v0
	v_or_b32_e32 v4, 24, v9
	v_cmp_lt_u32_e64 s[54:55], v4, v0
	v_or_b32_e32 v4, 25, v9
	v_or_b32_e32 v5, 26, v9
	v_cmp_lt_u32_e64 s[56:57], v4, v0
	v_cmp_lt_u32_e64 s[58:59], v5, v0
	v_or_b32_e32 v0, 40, v9
	s_and_b64 s[20:21], vcc, s[4:5]
	v_cmp_lt_u32_e32 vcc, v9, v6
	v_cmp_ge_u32_e64 s[4:5], v0, v7
	v_writelane_b32 v255, s0, 12
	s_and_b64 s[38:39], s[4:5], vcc
	v_cmp_ge_u32_e32 vcc, v15, v7
	v_cmp_lt_u32_e64 s[4:5], v15, v26
	v_add_u32_e32 v0, s8, v176
	s_movk_i32 s8, 0x7c
	v_writelane_b32 v255, s1, 13
	v_or_b32_e32 v17, 43, v9
	s_and_b64 s[0:1], vcc, s[4:5]
	v_cmp_ge_u32_e32 vcc, v16, v7
	v_cmp_lt_u32_e64 s[4:5], v16, v26
	v_sub_u32_e32 v0, v0, v1
	v_mul_lo_u32 v1, v3, s8
	v_and_or_b32 v8, v8, 3, v9
	v_or_b32_e32 v18, 48, v9
	v_or_b32_e32 v19, 49, v9
	v_or_b32_e32 v20, 50, v9
	v_or_b32_e32 v21, 51, v9
	v_or_b32_e32 v22, 56, v9
	v_or_b32_e32 v23, 57, v9
	v_or_b32_e32 v24, 58, v9
	v_or_b32_e32 v25, 59, v9
	v_cmp_ge_u32_e64 s[84:85], v14, v7
	s_and_b64 s[40:41], vcc, s[4:5]
	v_cmp_ge_u32_e32 vcc, v17, v7
	v_cmp_lt_u32_e64 s[4:5], v17, v26
	v_sub_u32_e32 v0, v0, v1
	v_mov_b32_e32 v14, v2
	v_mov_b32_e32 v15, v2
	v_cmp_ge_u32_e64 s[70:71], v9, v6
	v_cmp_ge_u32_e64 s[72:73], v4, v7
	v_cmp_ge_u32_e64 s[74:75], v5, v7
	v_cmp_ge_u32_e64 s[76:77], v10, v7
	v_cmp_ge_u32_e64 s[78:79], v11, v7
	v_cmp_ge_u32_e64 s[80:81], v12, v7
	v_cmp_ge_u32_e64 s[82:83], v13, v7
	s_and_b64 s[42:43], vcc, s[4:5]
	v_cmp_lt_u32_e64 s[86:87], v18, v26
	v_cmp_lt_u32_e64 s[88:89], v19, v26
	v_cmp_lt_u32_e64 s[90:91], v20, v26
	v_cmp_lt_u32_e64 s[92:93], v21, v26
	v_cmp_lt_u32_e64 s[94:95], v22, v26
	v_cmp_lt_u32_e64 s[96:97], v23, v26
	v_cmp_lt_u32_e64 s[4:5], v24, v26
	v_cmp_lt_u32_e64 s[6:7], v25, v26
	v_mul_u32_u24_e32 v184, 0x90, v8
	v_add_u32_e32 v185, 0x9190, v0
	v_mov_b32_e32 v0, v2
	v_mov_b32_e32 v1, v2
	v_mov_b32_e32 v3, v2
	v_mov_b32_e32 v4, v2
	v_mov_b32_e32 v5, v2
	v_mov_b32_e32 v6, v2
	v_mov_b32_e32 v7, v2
	v_mov_b32_e32 v8, v2
	v_mov_b32_e32 v9, v2
	v_mov_b32_e32 v10, v2
	v_mov_b32_e32 v11, v2
	v_mov_b32_e32 v12, v2
	v_mov_b32_e32 v13, v2
	v_mov_b64_e32 v[30:31], v[14:15]
	v_mov_b64_e32 v[46:47], v[14:15]
	v_mov_b64_e32 v[62:63], v[14:15]
	v_mov_b64_e32 v[78:79], v[14:15]
	v_add_u32_e32 v180, 8, v179
	v_mov_b32_e32 v177, 0
	v_mov_b32_e32 v186, 0xf149f2ca
	v_mov_b64_e32 v[28:29], v[12:13]
	v_mov_b64_e32 v[26:27], v[10:11]
	v_mov_b64_e32 v[24:25], v[8:9]
	v_mov_b64_e32 v[22:23], v[6:7]
	v_mov_b64_e32 v[20:21], v[4:5]
	v_mov_b64_e32 v[18:19], v[2:3]
	v_mov_b64_e32 v[16:17], v[0:1]
	v_mov_b64_e32 v[44:45], v[12:13]
	v_mov_b64_e32 v[42:43], v[10:11]
	v_mov_b64_e32 v[40:41], v[8:9]
	v_mov_b64_e32 v[38:39], v[6:7]
	v_mov_b64_e32 v[36:37], v[4:5]
	v_mov_b64_e32 v[34:35], v[2:3]
	v_mov_b64_e32 v[32:33], v[0:1]
	v_mov_b64_e32 v[60:61], v[12:13]
	v_mov_b64_e32 v[58:59], v[10:11]
	v_mov_b64_e32 v[56:57], v[8:9]
	v_mov_b64_e32 v[54:55], v[6:7]
	v_mov_b64_e32 v[52:53], v[4:5]
	v_mov_b64_e32 v[50:51], v[2:3]
	v_mov_b64_e32 v[48:49], v[0:1]
	v_mov_b64_e32 v[76:77], v[12:13]
	v_mov_b64_e32 v[74:75], v[10:11]
	v_mov_b64_e32 v[72:73], v[8:9]
	v_mov_b64_e32 v[70:71], v[6:7]
	v_mov_b64_e32 v[68:69], v[4:5]
	v_mov_b64_e32 v[66:67], v[2:3]
	v_mov_b64_e32 v[64:65], v[0:1]
	v_mov_b32_e32 v187, 0xf149f2ca
	v_mov_b32_e32 v183, 0
	v_lshrrev_b32_e32 v220, 3, v224
	v_and_b32_e32 v221, 7, v224
	v_lshlrev_b32_e32 v222, 12, v220
	v_mul_u32_u24_e32 v220, 0x90, v220
	v_lshl_add_u32 v220, v221, 4, v220
	v_lshl_or_b32 v221, v221, 4, v222
.LBB0_653:
	s_and_b32 s46, s33, 1
	s_add_i32 s29, s33, 1
	s_cmp_ge_u32 s29, s27
	s_cselect_b64 s[44:45], -1, 0
	s_and_b64 vcc, exec, s[44:45]
	s_cbranch_vccnz .LBB0_659
	s_xor_b32 s8, s46, 1
	s_mul_i32 s47, s8, 0x4800
	v_add_u32_e32 v0, s47, v220
	s_waitcnt vmcnt(1)
	ds_write_b128 v0, v[164:167]
	s_waitcnt vmcnt(0)
	ds_write_b128 v0, v[168:171] offset:9216
.LBB0_659:
	s_add_i32 s8, s33, 2
	s_cmp_ge_u32 s8, s27
	s_cbranch_scc1 .LBB0_661
	s_lshl_b64 s[8:9], s[2:3], 12
	s_add_u32 s8, s8, s36
	s_addc_u32 s9, s9, s37
	global_load_dwordx4 v[164:167], v221, s[8:9] offset:2048
	global_load_dwordx4 v[168:171], v221, s[8:9] offset:3072

; template <int DK, int DV, int MODE>
; DI void att_gload(const AttArgs& a, int tile, u32x4 (&kr)[(64 * (DK / 8) + NT - 1) / NT], u32x4 (&vr)[(64 * (DV / 8) + NT - 1) / NT]) {
;   constexpr int CK = DK / 8, CV = DV / 8;
;   constexpr int NKL = (64 * CK + NT - 1) / NT, NVL = (64 * CV + NT - 1) / NT;
;   const int t = tid_opaque();
;   const int kbase = tile * 64;
; #pragma unroll
;   for (int i = 0; i < NKL; ++i) {
; template <int DK, int DV, int MODE, int QB, bool PACK = false>
; DI void attn_item(const AttArgs& a, int q0, int t_lo, int t_hi) {
;     ...
;   const int t = tid_opaque(), l = t & 63, w = t >> 6, r = l & 31, h = l >> 5;
;   float* rpbs = (float*)(smem + 2 * BUFB);
;   const int hg = PACK ? (w >> 1) : 0;
;   const int wq0 = PACK ? q0 + (w & 1) * (32 * QB) : q0 + w * (32 * QB);
;   int rq = 0, r0 = 0, cq[QB], c0[QB];
; #pragma unroll
;   for (int qb = 0; qb < QB; ++qb) { cq[qb] = 0; c0[qb] = 0; }
;   if constexpr (MODE == 2) {
;     rq = wq0 >> 6;
;     r0 = min(max(rq - 4, 0), 24);
; #pragma unroll
;     for (int qb = 0; qb < QB; ++qb) {
;       cq[qb] = ((wq0 + qb * 32) & 63) + r;
;       c0[qb] = min(max(cq[qb] - 8, 0), 48);
;     }
;     for (int i = t; i < 465; i += NT) rpbs[i] = a.rpb[i];
;   }
;   bf16x8 qf[QB][NKS];
; #pragma unroll
;   for (int qb = 0; qb < QB; ++qb) {
;     const bf16_t* qp = a.q + hg * DK + (size_t)(wq0 + qb * 32 + r) * a.ldq + h * 8;
; #pragma unroll
;     for (int s = 0; s < NKS; ++s) qf[qb][s] = *(const bf16x8*)(qp + s * 16);
;   }
;   f32x16 o[QB][NDB];
;   float m[QB], lsum[QB];
; #pragma unroll
;   for (int qb = 0; qb < QB; ++qb) {
;     m[qb] = -1e30f; lsum[qb] = 0.f;
; #pragma unroll
;     for (int d = 0; d < NDB; ++d)
; #pragma unroll
;       for (int i = 0; i < 16; ++i) o[qb][d][i] = 0.f;
;   }
;   u32x4 kr[NKL], vr[NVL];
;   att_gload<DK, DV, MODE>(a, t_lo, kr, vr);
;   att_swrite<DK, DV>(0, kr, vr);
;   if (t_lo + 1 < t_hi) att_gload<DK, DV, MODE>(a, t_lo + 1, kr, vr);
;   __syncthreads();
;   const float scale = a.scale;
;   const float cexp = (MODE == 2) ? LOG2E : a.scale * LOG2E;
;   const int vq = (l & 15) >> 2, vp = l & 3, vblk = (l >> 4) & 1;
;   for (int tile = t_lo; tile < t_hi; ++tile) {
;     const int buf = (tile - t_lo) & 1;
;     if (tile + 1 < t_hi) att_swrite<DK, DV>(buf ^ 1, kr, vr);
;     if (tile + 2 < t_hi) att_gload<DK, DV, MODE>(a, tile + 2, kr, vr);
.LBB0_807:
	s_cmp_ge_u32 s4, s9
	s_waitcnt lgkmcnt(0)
	s_barrier
	s_cbranch_scc1 .LBB0_826
	s_and_b32 s0, s29, 15
	s_lshl_b32 s0, s0, 7
	s_min_u32 s1, s0, 0x80
	v_and_b32_e32 v5, 16, v3
	v_lshrrev_b32_e32 v6, 2, v3
	v_add_u32_e32 v215, 0xffffff80, v4
	v_add_u32_e32 v216, 0xbf, v4
	v_lshlrev_b32_e32 v4, 2, v187
	v_lshlrev_b32_e32 v3, 2, v3
	v_mul_u32_u24_e32 v218, 0x90, v1
	v_or_b32_e32 v1, s1, v1
	v_and_or_b32 v6, v6, 3, v4
	v_and_or_b32 v3, v3, 12, v5
	v_sub_u32_e32 v1, v4, v1
	v_mov_b32_e32 v14, v2
	v_mov_b32_e32 v15, v2
	s_sub_i32 s20, s0, s1
	v_lshlrev_b32_e32 v217, 1, v3
	v_mul_u32_u24_e32 v219, 0x90, v6
	v_sub_u32_e32 v190, v1, v0
	v_mov_b32_e32 v0, v2
	v_mov_b32_e32 v1, v2
	v_mov_b32_e32 v3, v2
	v_mov_b32_e32 v4, v2
	v_mov_b32_e32 v5, v2
	v_mov_b32_e32 v6, v2
	v_mov_b32_e32 v7, v2
	v_mov_b32_e32 v8, v2
	v_mov_b32_e32 v9, v2
	v_mov_b32_e32 v10, v2
	v_mov_b32_e32 v11, v2
	v_mov_b32_e32 v12, v2
	v_mov_b32_e32 v13, v2
	v_mov_b32_e32 v192, 0xf149f2ca
	v_mov_b64_e32 v[30:31], v[14:15]
	v_mov_b64_e32 v[46:47], v[14:15]
	v_mov_b64_e32 v[62:63], v[14:15]
	v_mov_b64_e32 v[78:79], v[14:15]
	s_add_i32 s21, s20, 0x80
	v_mov_b32_e32 v191, v2
	v_mov_b32_e32 v212, 0
	s_mov_b64 s[36:37], 0
	v_mov_b64_e32 v[28:29], v[12:13]
	v_mov_b64_e32 v[26:27], v[10:11]
	v_mov_b64_e32 v[24:25], v[8:9]
	v_mov_b64_e32 v[22:23], v[6:7]
	v_mov_b64_e32 v[20:21], v[4:5]
	v_mov_b64_e32 v[18:19], v[2:3]
	v_mov_b64_e32 v[16:17], v[0:1]
	v_mov_b64_e32 v[44:45], v[12:13]
	v_mov_b64_e32 v[42:43], v[10:11]
	v_mov_b64_e32 v[40:41], v[8:9]
	v_mov_b64_e32 v[38:39], v[6:7]
	v_mov_b64_e32 v[36:37], v[4:5]
	v_mov_b64_e32 v[34:35], v[2:3]
	v_mov_b64_e32 v[32:33], v[0:1]
	v_mov_b64_e32 v[60:61], v[12:13]
	v_mov_b64_e32 v[58:59], v[10:11]
	v_mov_b64_e32 v[56:57], v[8:9]
	v_mov_b64_e32 v[54:55], v[6:7]
	v_mov_b64_e32 v[52:53], v[4:5]
	v_mov_b64_e32 v[50:51], v[2:3]
	v_mov_b64_e32 v[48:49], v[0:1]
	v_mov_b64_e32 v[76:77], v[12:13]
	v_mov_b64_e32 v[74:75], v[10:11]
	v_mov_b64_e32 v[72:73], v[8:9]
	v_mov_b64_e32 v[70:71], v[6:7]
	v_mov_b64_e32 v[68:69], v[4:5]
	v_mov_b64_e32 v[66:67], v[2:3]
	v_mov_b64_e32 v[64:65], v[0:1]
	v_mov_b32_e32 v214, 0
	v_mov_b32_e32 v193, v192
	v_lshrrev_b32_e32 v220, 3, v224
	v_and_b32_e32 v221, 7, v224
	v_lshlrev_b32_e32 v222, 12, v220
	v_mul_u32_u24_e32 v220, 0x90, v220
	v_lshl_add_u32 v220, v221, 4, v220
	v_lshl_or_b32 v221, v221, 4, v222
.LBB0_809:
	s_and_b32 s25, s4, 1
	s_add_i32 s24, s4, 1
	s_cmp_ge_u32 s24, s9
	s_cselect_b64 s[2:3], -1, 0
	s_and_b64 vcc, exec, s[2:3]
	s_cbranch_vccnz .LBB0_815
	s_xor_b32 s0, s25, 1
	s_mul_i32 s5, s0, 0x4800
	v_add_u32_e32 v0, s5, v220
	s_waitcnt vmcnt(1)
	ds_write_b128 v0, v[176:179]
	s_waitcnt vmcnt(0)
	ds_write_b128 v0, v[180:183] offset:9216
.LBB0_815:
	s_add_i32 s0, s4, 2
	s_cmp_ge_u32 s0, s9
	s_cbranch_scc1 .LBB0_817
	s_add_u32 s0, s21, s36
	s_addc_u32 s1, 0, s37
	s_lshl_b64 s[0:1], s[0:1], 12
	s_add_u32 s0, s0, s30
	s_addc_u32 s1, s1, s31
	global_load_dwordx4 v[176:179], v221, s[0:1] offset:2560
	global_load_dwordx4 v[180:183], v221, s[0:1] offset:2816
